# as best + s_setprio 1 for waves 0-3 only during their post-barrier last-4-MFMA + DMA fast path (D loops)
# speedup vs baseline: 1.0041x; 1.0002x over previous
; #define SBAR() __builtin_amdgcn_sched_barrier(0)
; template <int D0> __device__ __forceinline__ void pv_one(f32x16& od, int vb, bf16x8 pa0, bf16x8 pa1, bf16x8 pa2, bf16x8 pa3) {
;     const s16x4 l0 = tr_read<v_rd_off(D0, 0, 0)>(vb), h0 = tr_read<v_rd_off(D0, 0, 1)>(vb), l1 = tr_read<v_rd_off(D0, 1, 0)>(vb), h1 = tr_read<v_rd_off(D0, 1, 1)>(vb);
;     const s16x4 l2 = tr_read<v_rd_off(D0, 2, 0)>(vb), h2 = tr_read<v_rd_off(D0, 2, 1)>(vb), l3 = tr_read<v_rd_off(D0, 3, 0)>(vb), h3 = tr_read<v_rd_off(D0, 3, 1)>(vb);
;     asm volatile("s_waitcnt lgkmcnt(0)" ::: "memory"); SBAR();
;     ...
;     od = __builtin_amdgcn_mfma_f32_32x32x16_bf16(pa0, PK(l0, h0), od, 0, 0, 0);
;     od = __builtin_amdgcn_mfma_f32_32x32x16_bf16(pa1, PK(l1, h1), od, 0, 0, 0);
;     od = __builtin_amdgcn_mfma_f32_32x32x16_bf16(pa2, PK(l2, h2), od, 0, 0, 0);
;     od = __builtin_amdgcn_mfma_f32_32x32x16_bf16(pa3, PK(l3, h3), od, 0, 0, 0);
;     ...
; }
; template <bool RSM> __device__ __forceinline__ void pv_d0(f32x16* o, f32x16& lacc, int vb, bf16x8 pa0, bf16x8 pa1, bf16x8 pa2, bf16x8 pa3) {
;     if (RSM) {
;         const bf16x8 ones = {0x3F80, 0x3F80, 0x3F80, 0x3F80, 0x3F80, 0x3F80, 0x3F80, 0x3F80};
;         lacc = __builtin_amdgcn_mfma_f32_32x32x16_bf16(pa0, ones, lacc, 0, 0, 0);
;         lacc = __builtin_amdgcn_mfma_f32_32x32x16_bf16(pa1, ones, lacc, 0, 0, 0);
;         lacc = __builtin_amdgcn_mfma_f32_32x32x16_bf16(pa2, ones, lacc, 0, 0, 0);
;         lacc = __builtin_amdgcn_mfma_f32_32x32x16_bf16(pa3, ones, lacc, 0, 0, 0); }
;     pv_one<0>(o[0], vb, pa0, pa1, pa2, pa3); pv_one<1>(o[1], vb, pa0, pa1, pa2, pa3); pv_one<2>(o[2], vb, pa0, pa1, pa2, pa3); pv_one<3>(o[3], vb, pa0, pa1, pa2, pa3);
; }
.LBB0_704:
	s_mov_b32 s38, s36
	s_mov_b32 s39, s36
	s_mov_b32 s37, s36
	v_mov_b64_e32 v[134:135], s[38:39]
	v_mov_b64_e32 v[132:133], s[36:37]
	s_lshl_b32 s23, s35, 14
	v_add_u32_e32 v0, s23, v230
	v_mfma_f32_32x32x16_bf16 v[96:111], v[6:9], v[132:135], v[96:111]
	ds_read_b64_tr_b16 v[136:137], v0 offset:0
	ds_read_b64_tr_b16 v[138:139], v0 offset:0x800
	ds_read_b64_tr_b16 v[140:141], v0 offset:0x1000
	ds_read_b64_tr_b16 v[142:143], v0 offset:0x1800
	ds_read_b64_tr_b16 v[192:193], v0 offset:0x2000
	ds_read_b64_tr_b16 v[194:195], v0 offset:0x2800
	ds_read_b64_tr_b16 v[196:197], v0 offset:0x3000
	v_mfma_f32_32x32x16_bf16 v[96:111], v[2:5], v[132:135], v[96:111]
	ds_read_b64_tr_b16 v[198:199], v0 offset:0x3800
	s_waitcnt lgkmcnt(0)
	v_mfma_f32_32x32x16_bf16 v[96:111], v[128:131], v[132:135], v[96:111]
	v_mfma_f32_32x32x16_bf16 v[96:111], v[10:13], v[132:135], v[96:111]
	v_mfma_f32_32x32x16_bf16 v[80:95], v[6:9], v[136:139], v[80:95]
	ds_read_b64_tr_b16 v[132:133], v0 offset:0x200
	ds_read_b64_tr_b16 v[134:135], v0 offset:0xa00
	ds_read_b64_tr_b16 v[136:137], v0 offset:0x1200
	ds_read_b64_tr_b16 v[138:139], v0 offset:0x1a00
	v_mfma_f32_32x32x16_bf16 v[80:95], v[2:5], v[140:143], v[80:95]
	ds_read_b64_tr_b16 v[140:141], v0 offset:0x2200
	ds_read_b64_tr_b16 v[142:143], v0 offset:0x2a00
	v_mfma_f32_32x32x16_bf16 v[80:95], v[128:131], v[192:195], v[80:95]
	ds_read_b64_tr_b16 v[192:193], v0 offset:0x3200
	ds_read_b64_tr_b16 v[194:195], v0 offset:0x3a00
	s_waitcnt lgkmcnt(0)
	v_mfma_f32_32x32x16_bf16 v[80:95], v[10:13], v[196:199], v[80:95]
	v_mfma_f32_32x32x16_bf16 v[64:79], v[6:9], v[132:135], v[64:79]
	ds_read_b64_tr_b16 v[132:133], v0 offset:0x400
	ds_read_b64_tr_b16 v[134:135], v0 offset:0xc00
	v_mfma_f32_32x32x16_bf16 v[64:79], v[2:5], v[136:139], v[64:79]
	ds_read_b64_tr_b16 v[136:137], v0 offset:0x1400
	ds_read_b64_tr_b16 v[138:139], v0 offset:0x1c00
	v_mfma_f32_32x32x16_bf16 v[64:79], v[128:131], v[140:143], v[64:79]
	ds_read_b64_tr_b16 v[140:141], v0 offset:0x2400
	ds_read_b64_tr_b16 v[142:143], v0 offset:0x2c00
	v_mfma_f32_32x32x16_bf16 v[64:79], v[10:13], v[192:195], v[64:79]
	ds_read_b64_tr_b16 v[192:193], v0 offset:0x3400
	ds_read_b64_tr_b16 v[194:195], v0 offset:0x3c00
	s_waitcnt lgkmcnt(0)
	v_mfma_f32_32x32x16_bf16 v[48:63], v[6:9], v[132:135], v[48:63]
	ds_read_b64_tr_b16 v[132:133], v0 offset:0x600
	ds_read_b64_tr_b16 v[134:135], v0 offset:0xe00
	v_mfma_f32_32x32x16_bf16 v[48:63], v[2:5], v[136:139], v[48:63]
	ds_read_b64_tr_b16 v[136:137], v0 offset:0x1600
	ds_read_b64_tr_b16 v[138:139], v0 offset:0x1e00
	v_mfma_f32_32x32x16_bf16 v[48:63], v[128:131], v[140:143], v[48:63]
	ds_read_b64_tr_b16 v[140:141], v0 offset:0x2600
	ds_read_b64_tr_b16 v[142:143], v0 offset:0x2e00
	v_mfma_f32_32x32x16_bf16 v[48:63], v[10:13], v[192:195], v[48:63]
	ds_read_b64_tr_b16 v[192:193], v0 offset:0x3600
	ds_read_b64_tr_b16 v[194:195], v0 offset:0x3e00
	s_waitcnt lgkmcnt(0)
	s_and_b64 vcc, exec, s[0:1]
	s_cbranch_vccnz .Lmy_slow_0
	s_cmpk_gt_u32 s57, 0xfc
	s_cbranch_scc1 .Lmy_slow_0
	s_mov_b64 s[20:21], -1
	s_add_i32 m0, s81, s22
	s_addk_i32 s23, 0xc000
	s_cmp_gt_i32 s35, 0
	s_cselect_b32 s20, s23, 0xc000
	s_waitcnt vmcnt(3) lgkmcnt(0)
	s_barrier
	s_setprio 1
	v_mfma_f32_32x32x16_bf16 v[32:47], v[6:9], v[132:135], v[32:47]
	s_and_b64 vcc, exec, s[0:1]
	v_mfma_f32_32x32x16_bf16 v[32:47], v[2:5], v[136:139], v[32:47]
	v_mfma_f32_32x32x16_bf16 v[32:47], v[128:131], v[140:143], v[32:47]
	v_mfma_f32_32x32x16_bf16 v[32:47], v[10:13], v[192:195], v[32:47]
	s_add_i32 s20, s63, s20
	global_load_lds_dwordx4 v[214:215], off
	s_mov_b32 m0, s20
	v_lshl_add_u64 v[214:215], v[214:215], 0, s[74:75]
	global_load_lds_dwordx4 v[212:213], off
	s_add_i32 m0, s20, 0x2000
	v_lshl_add_u64 v[2:3], v[212:213], 0, s[74:75]
	global_load_lds_dwordx4 v[216:217], off
	v_lshl_add_u64 v[4:5], v[216:217], 0, s[74:75]
	v_mov_b64_e32 v[216:217], v[4:5]
	v_mov_b64_e32 v[212:213], v[2:3]
	s_setprio 0
	s_branch .LBB0_709

; #define SBAR() __builtin_amdgcn_sched_barrier(0)
; template <int D0> __device__ __forceinline__ void pv_one(f32x16& od, int vb, bf16x8 pa0, bf16x8 pa1, bf16x8 pa2, bf16x8 pa3) {
;     const s16x4 l0 = tr_read<v_rd_off(D0, 0, 0)>(vb), h0 = tr_read<v_rd_off(D0, 0, 1)>(vb), l1 = tr_read<v_rd_off(D0, 1, 0)>(vb), h1 = tr_read<v_rd_off(D0, 1, 1)>(vb);
;     const s16x4 l2 = tr_read<v_rd_off(D0, 2, 0)>(vb), h2 = tr_read<v_rd_off(D0, 2, 1)>(vb), l3 = tr_read<v_rd_off(D0, 3, 0)>(vb), h3 = tr_read<v_rd_off(D0, 3, 1)>(vb);
;     asm volatile("s_waitcnt lgkmcnt(0)" ::: "memory"); SBAR();
;     ...
;     od = __builtin_amdgcn_mfma_f32_32x32x16_bf16(pa0, PK(l0, h0), od, 0, 0, 0);
;     od = __builtin_amdgcn_mfma_f32_32x32x16_bf16(pa1, PK(l1, h1), od, 0, 0, 0);
;     od = __builtin_amdgcn_mfma_f32_32x32x16_bf16(pa2, PK(l2, h2), od, 0, 0, 0);
;     od = __builtin_amdgcn_mfma_f32_32x32x16_bf16(pa3, PK(l3, h3), od, 0, 0, 0);
;     ...
; }
; template <bool RSM> __device__ __forceinline__ void pv_d0(f32x16* o, f32x16& lacc, int vb, bf16x8 pa0, bf16x8 pa1, bf16x8 pa2, bf16x8 pa3) {
;     if (RSM) {
;         const bf16x8 ones = {0x3F80, 0x3F80, 0x3F80, 0x3F80, 0x3F80, 0x3F80, 0x3F80, 0x3F80};
;         lacc = __builtin_amdgcn_mfma_f32_32x32x16_bf16(pa0, ones, lacc, 0, 0, 0);
;         lacc = __builtin_amdgcn_mfma_f32_32x32x16_bf16(pa1, ones, lacc, 0, 0, 0);
;         lacc = __builtin_amdgcn_mfma_f32_32x32x16_bf16(pa2, ones, lacc, 0, 0, 0);
;         lacc = __builtin_amdgcn_mfma_f32_32x32x16_bf16(pa3, ones, lacc, 0, 0, 0); }
;     pv_one<0>(o[0], vb, pa0, pa1, pa2, pa3); pv_one<1>(o[1], vb, pa0, pa1, pa2, pa3); pv_one<2>(o[2], vb, pa0, pa1, pa2, pa3); pv_one<3>(o[3], vb, pa0, pa1, pa2, pa3);
; }
.LBB0_719:
	s_mov_b32 s38, s36
	s_mov_b32 s39, s36
	s_mov_b32 s37, s36
	v_mov_b64_e32 v[150:151], s[38:39]
	v_mov_b64_e32 v[148:149], s[36:37]
	s_lshl_b32 s37, s35, 14
	v_add_u32_e32 v14, s37, v230
	v_mfma_f32_32x32x16_bf16 v[96:111], v[6:9], v[148:151], v[96:111]
	ds_read_b64_tr_b16 v[152:153], v14 offset:0
	ds_read_b64_tr_b16 v[154:155], v14 offset:0x800
	ds_read_b64_tr_b16 v[156:157], v14 offset:0x1000
	ds_read_b64_tr_b16 v[158:159], v14 offset:0x1800
	ds_read_b64_tr_b16 v[192:193], v14 offset:0x2000
	ds_read_b64_tr_b16 v[194:195], v14 offset:0x2800
	ds_read_b64_tr_b16 v[196:197], v14 offset:0x3000
	v_mfma_f32_32x32x16_bf16 v[96:111], v[2:5], v[148:151], v[96:111]
	ds_read_b64_tr_b16 v[198:199], v14 offset:0x3800
	s_waitcnt lgkmcnt(0)
	v_mfma_f32_32x32x16_bf16 v[96:111], v[144:147], v[148:151], v[96:111]
	v_mfma_f32_32x32x16_bf16 v[96:111], v[10:13], v[148:151], v[96:111]
	v_mfma_f32_32x32x16_bf16 v[80:95], v[6:9], v[152:155], v[80:95]
	ds_read_b64_tr_b16 v[148:149], v14 offset:0x200
	ds_read_b64_tr_b16 v[150:151], v14 offset:0xa00
	ds_read_b64_tr_b16 v[152:153], v14 offset:0x1200
	ds_read_b64_tr_b16 v[154:155], v14 offset:0x1a00
	v_mfma_f32_32x32x16_bf16 v[80:95], v[2:5], v[156:159], v[80:95]
	ds_read_b64_tr_b16 v[156:157], v14 offset:0x2200
	ds_read_b64_tr_b16 v[158:159], v14 offset:0x2a00
	v_mfma_f32_32x32x16_bf16 v[80:95], v[144:147], v[192:195], v[80:95]
	ds_read_b64_tr_b16 v[192:193], v14 offset:0x3200
	ds_read_b64_tr_b16 v[194:195], v14 offset:0x3a00
	s_waitcnt lgkmcnt(0)
	v_mfma_f32_32x32x16_bf16 v[80:95], v[10:13], v[196:199], v[80:95]
	v_mfma_f32_32x32x16_bf16 v[64:79], v[6:9], v[148:151], v[64:79]
	ds_read_b64_tr_b16 v[148:149], v14 offset:0x400
	ds_read_b64_tr_b16 v[150:151], v14 offset:0xc00
	v_mfma_f32_32x32x16_bf16 v[64:79], v[2:5], v[152:155], v[64:79]
	ds_read_b64_tr_b16 v[152:153], v14 offset:0x1400
	ds_read_b64_tr_b16 v[154:155], v14 offset:0x1c00
	v_mfma_f32_32x32x16_bf16 v[64:79], v[144:147], v[156:159], v[64:79]
	ds_read_b64_tr_b16 v[156:157], v14 offset:0x2400
	ds_read_b64_tr_b16 v[158:159], v14 offset:0x2c00
	v_mfma_f32_32x32x16_bf16 v[64:79], v[10:13], v[192:195], v[64:79]
	ds_read_b64_tr_b16 v[192:193], v14 offset:0x3400
	ds_read_b64_tr_b16 v[194:195], v14 offset:0x3c00
	s_waitcnt lgkmcnt(0)
	v_mfma_f32_32x32x16_bf16 v[48:63], v[6:9], v[148:151], v[48:63]
	ds_read_b64_tr_b16 v[148:149], v14 offset:0x600
	ds_read_b64_tr_b16 v[150:151], v14 offset:0xe00
	v_mfma_f32_32x32x16_bf16 v[48:63], v[2:5], v[152:155], v[48:63]
	ds_read_b64_tr_b16 v[152:153], v14 offset:0x1600
	ds_read_b64_tr_b16 v[154:155], v14 offset:0x1e00
	v_mfma_f32_32x32x16_bf16 v[48:63], v[144:147], v[156:159], v[48:63]
	ds_read_b64_tr_b16 v[156:157], v14 offset:0x2600
	ds_read_b64_tr_b16 v[158:159], v14 offset:0x2e00
	v_mfma_f32_32x32x16_bf16 v[48:63], v[10:13], v[192:195], v[48:63]
	ds_read_b64_tr_b16 v[192:193], v14 offset:0x3600
	ds_read_b64_tr_b16 v[194:195], v14 offset:0x3e00
	s_waitcnt lgkmcnt(0)
	s_and_b64 vcc, exec, s[0:1]
	s_cbranch_vccnz .Lmy_slow_1
	s_cmpk_gt_u32 s57, 0xfb
	s_cbranch_scc1 .Lmy_slow_1
	s_mov_b64 s[22:23], -1
	s_add_i32 m0, s81, s78
	s_addk_i32 s37, 0xc000
	s_cmp_gt_i32 s35, 0
	s_cselect_b32 s22, s37, 0xc000
	s_waitcnt vmcnt(3) lgkmcnt(0)
	s_barrier
	s_setprio 1
	v_mfma_f32_32x32x16_bf16 v[32:47], v[6:9], v[148:151], v[32:47]
	s_and_b64 vcc, exec, s[0:1]
	v_mfma_f32_32x32x16_bf16 v[32:47], v[2:5], v[152:155], v[32:47]
	v_mfma_f32_32x32x16_bf16 v[32:47], v[144:147], v[156:159], v[32:47]
	v_mfma_f32_32x32x16_bf16 v[32:47], v[10:13], v[192:195], v[32:47]
	s_add_i32 s22, s63, s22
	global_load_lds_dwordx4 v[214:215], off
	s_mov_b32 m0, s22
	v_lshl_add_u64 v[214:215], v[214:215], 0, s[74:75]
	global_load_lds_dwordx4 v[212:213], off
	s_add_i32 m0, s22, 0x2000
	v_lshl_add_u64 v[2:3], v[212:213], 0, s[74:75]
	global_load_lds_dwordx4 v[216:217], off
	v_lshl_add_u64 v[4:5], v[216:217], 0, s[74:75]
	v_mov_b64_e32 v[216:217], v[4:5]
	v_mov_b64_e32 v[212:213], v[2:3]
	s_setprio 0
	s_branch .LBB0_724

; #define SBAR() __builtin_amdgcn_sched_barrier(0)
; template <int D0> __device__ __forceinline__ void pv_one(f32x16& od, int vb, bf16x8 pa0, bf16x8 pa1, bf16x8 pa2, bf16x8 pa3) {
;     const s16x4 l0 = tr_read<v_rd_off(D0, 0, 0)>(vb), h0 = tr_read<v_rd_off(D0, 0, 1)>(vb), l1 = tr_read<v_rd_off(D0, 1, 0)>(vb), h1 = tr_read<v_rd_off(D0, 1, 1)>(vb);
;     const s16x4 l2 = tr_read<v_rd_off(D0, 2, 0)>(vb), h2 = tr_read<v_rd_off(D0, 2, 1)>(vb), l3 = tr_read<v_rd_off(D0, 3, 0)>(vb), h3 = tr_read<v_rd_off(D0, 3, 1)>(vb);
;     asm volatile("s_waitcnt lgkmcnt(0)" ::: "memory"); SBAR();
;     ...
;     od = __builtin_amdgcn_mfma_f32_32x32x16_bf16(pa0, PK(l0, h0), od, 0, 0, 0);
;     od = __builtin_amdgcn_mfma_f32_32x32x16_bf16(pa1, PK(l1, h1), od, 0, 0, 0);
;     od = __builtin_amdgcn_mfma_f32_32x32x16_bf16(pa2, PK(l2, h2), od, 0, 0, 0);
;     od = __builtin_amdgcn_mfma_f32_32x32x16_bf16(pa3, PK(l3, h3), od, 0, 0, 0);
;     ...
; }
; template <bool RSM> __device__ __forceinline__ void pv_d0(f32x16* o, f32x16& lacc, int vb, bf16x8 pa0, bf16x8 pa1, bf16x8 pa2, bf16x8 pa3) {
;     if (RSM) {
;         const bf16x8 ones = {0x3F80, 0x3F80, 0x3F80, 0x3F80, 0x3F80, 0x3F80, 0x3F80, 0x3F80};
;         lacc = __builtin_amdgcn_mfma_f32_32x32x16_bf16(pa0, ones, lacc, 0, 0, 0);
;         lacc = __builtin_amdgcn_mfma_f32_32x32x16_bf16(pa1, ones, lacc, 0, 0, 0);
;         lacc = __builtin_amdgcn_mfma_f32_32x32x16_bf16(pa2, ones, lacc, 0, 0, 0);
;         lacc = __builtin_amdgcn_mfma_f32_32x32x16_bf16(pa3, ones, lacc, 0, 0, 0); }
;     pv_one<0>(o[0], vb, pa0, pa1, pa2, pa3); pv_one<1>(o[1], vb, pa0, pa1, pa2, pa3); pv_one<2>(o[2], vb, pa0, pa1, pa2, pa3); pv_one<3>(o[3], vb, pa0, pa1, pa2, pa3);
; }
.LBB0_779:
	s_mov_b32 s38, s36
	s_mov_b32 s39, s36
	s_mov_b32 s37, s36
	v_mov_b64_e32 v[118:119], s[38:39]
	v_mov_b64_e32 v[116:117], s[36:37]
	s_lshl_b32 s15, s18, 14
	v_add_u32_e32 v0, s15, v192
	v_mfma_f32_32x32x16_bf16 v[80:95], v[6:9], v[116:119], v[80:95]
	ds_read_b64_tr_b16 v[120:121], v0 offset:0
	ds_read_b64_tr_b16 v[122:123], v0 offset:0x800
	ds_read_b64_tr_b16 v[124:125], v0 offset:0x1000
	ds_read_b64_tr_b16 v[126:127], v0 offset:0x1800
	ds_read_b64_tr_b16 v[176:177], v0 offset:0x2000
	ds_read_b64_tr_b16 v[178:179], v0 offset:0x2800
	ds_read_b64_tr_b16 v[180:181], v0 offset:0x3000
	v_mfma_f32_32x32x16_bf16 v[80:95], v[2:5], v[116:119], v[80:95]
	ds_read_b64_tr_b16 v[182:183], v0 offset:0x3800
	s_waitcnt lgkmcnt(0)
	v_mfma_f32_32x32x16_bf16 v[80:95], v[112:115], v[116:119], v[80:95]
	v_mfma_f32_32x32x16_bf16 v[80:95], v[10:13], v[116:119], v[80:95]
	v_mfma_f32_32x32x16_bf16 v[64:79], v[6:9], v[120:123], v[64:79]
	ds_read_b64_tr_b16 v[116:117], v0 offset:0x200
	ds_read_b64_tr_b16 v[118:119], v0 offset:0xa00
	ds_read_b64_tr_b16 v[120:121], v0 offset:0x1200
	ds_read_b64_tr_b16 v[122:123], v0 offset:0x1a00
	v_mfma_f32_32x32x16_bf16 v[64:79], v[2:5], v[124:127], v[64:79]
	ds_read_b64_tr_b16 v[124:125], v0 offset:0x2200
	ds_read_b64_tr_b16 v[126:127], v0 offset:0x2a00
	v_mfma_f32_32x32x16_bf16 v[64:79], v[112:115], v[176:179], v[64:79]
	ds_read_b64_tr_b16 v[176:177], v0 offset:0x3200
	ds_read_b64_tr_b16 v[178:179], v0 offset:0x3a00
	s_waitcnt lgkmcnt(0)
	v_mfma_f32_32x32x16_bf16 v[64:79], v[10:13], v[180:183], v[64:79]
	v_mfma_f32_32x32x16_bf16 v[48:63], v[6:9], v[116:119], v[48:63]
	ds_read_b64_tr_b16 v[116:117], v0 offset:0x400
	ds_read_b64_tr_b16 v[118:119], v0 offset:0xc00
	v_mfma_f32_32x32x16_bf16 v[48:63], v[2:5], v[120:123], v[48:63]
	ds_read_b64_tr_b16 v[120:121], v0 offset:0x1400
	ds_read_b64_tr_b16 v[122:123], v0 offset:0x1c00
	v_mfma_f32_32x32x16_bf16 v[48:63], v[112:115], v[124:127], v[48:63]
	ds_read_b64_tr_b16 v[124:125], v0 offset:0x2400
	ds_read_b64_tr_b16 v[126:127], v0 offset:0x2c00
	v_mfma_f32_32x32x16_bf16 v[48:63], v[10:13], v[176:179], v[48:63]
	ds_read_b64_tr_b16 v[176:177], v0 offset:0x3400
	ds_read_b64_tr_b16 v[178:179], v0 offset:0x3c00
	s_waitcnt lgkmcnt(0)
	v_mfma_f32_32x32x16_bf16 v[32:47], v[6:9], v[116:119], v[32:47]
	ds_read_b64_tr_b16 v[116:117], v0 offset:0x600
	ds_read_b64_tr_b16 v[118:119], v0 offset:0xe00
	v_mfma_f32_32x32x16_bf16 v[32:47], v[2:5], v[120:123], v[32:47]
	ds_read_b64_tr_b16 v[120:121], v0 offset:0x1600
	ds_read_b64_tr_b16 v[122:123], v0 offset:0x1e00
	v_mfma_f32_32x32x16_bf16 v[32:47], v[112:115], v[124:127], v[32:47]
	ds_read_b64_tr_b16 v[124:125], v0 offset:0x2600
	ds_read_b64_tr_b16 v[126:127], v0 offset:0x2e00
	v_mfma_f32_32x32x16_bf16 v[32:47], v[10:13], v[176:179], v[32:47]
	ds_read_b64_tr_b16 v[176:177], v0 offset:0x3600
	ds_read_b64_tr_b16 v[178:179], v0 offset:0x3e00
	s_waitcnt lgkmcnt(0)
	s_and_b64 vcc, exec, s[0:1]
	s_cbranch_vccnz .Lmy_slow_2
	s_cmpk_gt_u32 s17, 0xfc
	s_cbranch_scc1 .Lmy_slow_2
	s_mov_b64 s[12:13], -1
	s_add_i32 m0, s81, s14
	s_addk_i32 s15, 0xc000
	s_cmp_gt_i32 s18, 0
	s_cselect_b32 s12, s15, 0xc000
	s_waitcnt vmcnt(3) lgkmcnt(0)
	s_barrier
	s_setprio 1
	v_mfma_f32_32x32x16_bf16 v[16:31], v[6:9], v[116:119], v[16:31]
	s_and_b64 vcc, exec, s[0:1]
	v_mfma_f32_32x32x16_bf16 v[16:31], v[2:5], v[120:123], v[16:31]
	v_mfma_f32_32x32x16_bf16 v[16:31], v[112:115], v[124:127], v[16:31]
	v_mfma_f32_32x32x16_bf16 v[16:31], v[10:13], v[176:179], v[16:31]
	s_add_i32 s12, s63, s12
	global_load_lds_dwordx4 v[184:185], off
	s_mov_b32 m0, s12
	v_lshl_add_u64 v[184:185], v[184:185], 0, s[74:75]
	global_load_lds_dwordx4 v[186:187], off
	s_add_i32 m0, s12, 0x2000
	v_lshl_add_u64 v[2:3], v[186:187], 0, s[74:75]
	global_load_lds_dwordx4 v[188:189], off
	v_lshl_add_u64 v[4:5], v[188:189], 0, s[74:75]
	v_mov_b64_e32 v[188:189], v[4:5]
	v_mov_b64_e32 v[186:187], v[2:3]
	s_setprio 0
	s_branch .LBB0_784

; #define SBAR() __builtin_amdgcn_sched_barrier(0)
; template <int D0> __device__ __forceinline__ void pv_one(f32x16& od, int vb, bf16x8 pa0, bf16x8 pa1, bf16x8 pa2, bf16x8 pa3) {
;     const s16x4 l0 = tr_read<v_rd_off(D0, 0, 0)>(vb), h0 = tr_read<v_rd_off(D0, 0, 1)>(vb), l1 = tr_read<v_rd_off(D0, 1, 0)>(vb), h1 = tr_read<v_rd_off(D0, 1, 1)>(vb);
;     const s16x4 l2 = tr_read<v_rd_off(D0, 2, 0)>(vb), h2 = tr_read<v_rd_off(D0, 2, 1)>(vb), l3 = tr_read<v_rd_off(D0, 3, 0)>(vb), h3 = tr_read<v_rd_off(D0, 3, 1)>(vb);
;     asm volatile("s_waitcnt lgkmcnt(0)" ::: "memory"); SBAR();
;     ...
;     od = __builtin_amdgcn_mfma_f32_32x32x16_bf16(pa0, PK(l0, h0), od, 0, 0, 0);
;     od = __builtin_amdgcn_mfma_f32_32x32x16_bf16(pa1, PK(l1, h1), od, 0, 0, 0);
;     od = __builtin_amdgcn_mfma_f32_32x32x16_bf16(pa2, PK(l2, h2), od, 0, 0, 0);
;     od = __builtin_amdgcn_mfma_f32_32x32x16_bf16(pa3, PK(l3, h3), od, 0, 0, 0);
;     ...
; }
; template <bool RSM> __device__ __forceinline__ void pv_d0(f32x16* o, f32x16& lacc, int vb, bf16x8 pa0, bf16x8 pa1, bf16x8 pa2, bf16x8 pa3) {
;     if (RSM) {
;         const bf16x8 ones = {0x3F80, 0x3F80, 0x3F80, 0x3F80, 0x3F80, 0x3F80, 0x3F80, 0x3F80};
;         lacc = __builtin_amdgcn_mfma_f32_32x32x16_bf16(pa0, ones, lacc, 0, 0, 0);
;         lacc = __builtin_amdgcn_mfma_f32_32x32x16_bf16(pa1, ones, lacc, 0, 0, 0);
;         lacc = __builtin_amdgcn_mfma_f32_32x32x16_bf16(pa2, ones, lacc, 0, 0, 0);
;         lacc = __builtin_amdgcn_mfma_f32_32x32x16_bf16(pa3, ones, lacc, 0, 0, 0); }
;     pv_one<0>(o[0], vb, pa0, pa1, pa2, pa3); pv_one<1>(o[1], vb, pa0, pa1, pa2, pa3); pv_one<2>(o[2], vb, pa0, pa1, pa2, pa3); pv_one<3>(o[3], vb, pa0, pa1, pa2, pa3);
; }
.LBB0_794:
	s_mov_b32 s38, s36
	s_mov_b32 s39, s36
	s_mov_b32 s37, s36
	v_mov_b64_e32 v[134:135], s[38:39]
	v_mov_b64_e32 v[132:133], s[36:37]
	s_lshl_b32 s31, s18, 14
	v_add_u32_e32 v14, s31, v192
	v_mfma_f32_32x32x16_bf16 v[80:95], v[6:9], v[132:135], v[80:95]
	ds_read_b64_tr_b16 v[136:137], v14 offset:0
	ds_read_b64_tr_b16 v[138:139], v14 offset:0x800
	ds_read_b64_tr_b16 v[140:141], v14 offset:0x1000
	ds_read_b64_tr_b16 v[142:143], v14 offset:0x1800
	ds_read_b64_tr_b16 v[176:177], v14 offset:0x2000
	ds_read_b64_tr_b16 v[178:179], v14 offset:0x2800
	ds_read_b64_tr_b16 v[180:181], v14 offset:0x3000
	v_mfma_f32_32x32x16_bf16 v[80:95], v[2:5], v[132:135], v[80:95]
	ds_read_b64_tr_b16 v[182:183], v14 offset:0x3800
	s_waitcnt lgkmcnt(0)
	v_mfma_f32_32x32x16_bf16 v[80:95], v[128:131], v[132:135], v[80:95]
	v_mfma_f32_32x32x16_bf16 v[80:95], v[10:13], v[132:135], v[80:95]
	v_mfma_f32_32x32x16_bf16 v[64:79], v[6:9], v[136:139], v[64:79]
	ds_read_b64_tr_b16 v[132:133], v14 offset:0x200
	ds_read_b64_tr_b16 v[134:135], v14 offset:0xa00
	ds_read_b64_tr_b16 v[136:137], v14 offset:0x1200
	ds_read_b64_tr_b16 v[138:139], v14 offset:0x1a00
	v_mfma_f32_32x32x16_bf16 v[64:79], v[2:5], v[140:143], v[64:79]
	ds_read_b64_tr_b16 v[140:141], v14 offset:0x2200
	ds_read_b64_tr_b16 v[142:143], v14 offset:0x2a00
	v_mfma_f32_32x32x16_bf16 v[64:79], v[128:131], v[176:179], v[64:79]
	ds_read_b64_tr_b16 v[176:177], v14 offset:0x3200
	ds_read_b64_tr_b16 v[178:179], v14 offset:0x3a00
	s_waitcnt lgkmcnt(0)
	v_mfma_f32_32x32x16_bf16 v[64:79], v[10:13], v[180:183], v[64:79]
	v_mfma_f32_32x32x16_bf16 v[48:63], v[6:9], v[132:135], v[48:63]
	ds_read_b64_tr_b16 v[132:133], v14 offset:0x400
	ds_read_b64_tr_b16 v[134:135], v14 offset:0xc00
	v_mfma_f32_32x32x16_bf16 v[48:63], v[2:5], v[136:139], v[48:63]
	ds_read_b64_tr_b16 v[136:137], v14 offset:0x1400
	ds_read_b64_tr_b16 v[138:139], v14 offset:0x1c00
	v_mfma_f32_32x32x16_bf16 v[48:63], v[128:131], v[140:143], v[48:63]
	ds_read_b64_tr_b16 v[140:141], v14 offset:0x2400
	ds_read_b64_tr_b16 v[142:143], v14 offset:0x2c00
	v_mfma_f32_32x32x16_bf16 v[48:63], v[10:13], v[176:179], v[48:63]
	ds_read_b64_tr_b16 v[176:177], v14 offset:0x3400
	ds_read_b64_tr_b16 v[178:179], v14 offset:0x3c00
	s_waitcnt lgkmcnt(0)
	v_mfma_f32_32x32x16_bf16 v[32:47], v[6:9], v[132:135], v[32:47]
	ds_read_b64_tr_b16 v[132:133], v14 offset:0x600
	ds_read_b64_tr_b16 v[134:135], v14 offset:0xe00
	v_mfma_f32_32x32x16_bf16 v[32:47], v[2:5], v[136:139], v[32:47]
	ds_read_b64_tr_b16 v[136:137], v14 offset:0x1600
	ds_read_b64_tr_b16 v[138:139], v14 offset:0x1e00
	v_mfma_f32_32x32x16_bf16 v[32:47], v[128:131], v[140:143], v[32:47]
	ds_read_b64_tr_b16 v[140:141], v14 offset:0x2600
	ds_read_b64_tr_b16 v[142:143], v14 offset:0x2e00
	v_mfma_f32_32x32x16_bf16 v[32:47], v[10:13], v[176:179], v[32:47]
	ds_read_b64_tr_b16 v[176:177], v14 offset:0x3600
	ds_read_b64_tr_b16 v[178:179], v14 offset:0x3e00
	s_waitcnt lgkmcnt(0)
	s_and_b64 vcc, exec, s[0:1]
	s_cbranch_vccnz .Lmy_slow_3
	s_cmpk_gt_u32 s17, 0xfb
	s_cbranch_scc1 .Lmy_slow_3
	s_mov_b64 s[14:15], -1
	s_add_i32 m0, s81, s26
	s_addk_i32 s31, 0xc000
	s_cmp_gt_i32 s18, 0
	s_cselect_b32 s14, s31, 0xc000
	s_waitcnt vmcnt(3) lgkmcnt(0)
	s_barrier
	s_setprio 1
	v_mfma_f32_32x32x16_bf16 v[16:31], v[6:9], v[132:135], v[16:31]
	s_and_b64 vcc, exec, s[0:1]
	v_mfma_f32_32x32x16_bf16 v[16:31], v[2:5], v[136:139], v[16:31]
	v_mfma_f32_32x32x16_bf16 v[16:31], v[128:131], v[140:143], v[16:31]
	v_mfma_f32_32x32x16_bf16 v[16:31], v[10:13], v[176:179], v[16:31]
	s_add_i32 s14, s63, s14
	global_load_lds_dwordx4 v[184:185], off
	s_mov_b32 m0, s14
	v_lshl_add_u64 v[184:185], v[184:185], 0, s[74:75]
	global_load_lds_dwordx4 v[186:187], off
	s_add_i32 m0, s14, 0x2000
	v_lshl_add_u64 v[2:3], v[186:187], 0, s[74:75]
	global_load_lds_dwordx4 v[188:189], off
	v_lshl_add_u64 v[4:5], v[188:189], 0, s[74:75]
	v_mov_b64_e32 v[188:189], v[4:5]
	v_mov_b64_e32 v[186:187], v[2:3]
	s_setprio 0
	s_branch .LBB0_799
